# strategy 7.4 mirror: one static s_setprio 1 for waves 0-3 at the start of the mixer phase
# speedup vs baseline: 1.0009x; 1.0009x over previous
.LBB0_1664:
	s_or_b64 exec, exec, s[0:1]
	v_readlane_b32 s0, v234, 0
	v_readlane_b32 s2, v234, 2
	v_readlane_b32 s1, v234, 1
	v_readlane_b32 s3, v234, 3
	s_add_u32 s0, s2, 0x32000000
	s_addc_u32 s1, s3, 0
	v_writelane_b32 v233, s0, 21
	s_waitcnt lgkmcnt(0)
	s_barrier
	v_readfirstlane_b32 s99, v183
	s_nop 3
	s_lshr_b32 s99, s99, 6
	s_cmp_lt_u32 s99, 4
	s_cbranch_scc0 .Lprio_mix_done
	s_setprio 1
